# SSD heavy waves static priority 3 instead of 2
# speedup vs baseline: 1.0040x; 1.0011x over previous
.LBB0_998:
	s_or_b64 exec, exec, s[0:1]
	v_readlane_b32 s0, v254, 43
	v_readlane_b32 s1, v254, 44
	v_readlane_b32 s2, v254, 45
	v_readlane_b32 s3, v254, 46
	s_and_b32 s1, s5, 0xffff
	v_writelane_b32 v254, s0, 43
	s_waitcnt vmcnt(0)
	v_mul_f32_e32 v0, 0x3fb8aa3b, v0
	v_exp_f32_e32 v135, v0
	v_writelane_b32 v254, s1, 44
	v_writelane_b32 v254, s2, 45
	v_writelane_b32 v254, s3, 46
	s_sub_i32 s0, 11, s12
	s_cmp_lt_i32 s12, 4
	s_cselect_b32 s22, s12, s0
	s_cmp_gt_i32 s22, 3
	s_cselect_b64 s[0:1], -1, 0
	v_writelane_b32 v255, s0, 14
	s_cmp_lt_i32 s22, 4
	s_nop 0
	v_writelane_b32 v255, s1, 15
	s_cbranch_scc0 .LBB0_1000
	s_setprio 3

.LBB0_1123:
	s_or_b64 exec, exec, s[2:3]
	v_readlane_b32 s8, v254, 43
	v_readlane_b32 s9, v254, 44
	s_and_b32 s9, s7, 0xffff
	s_sub_i32 s2, 11, s0
	s_cmp_lt_i32 s0, 4
	s_waitcnt vmcnt(0)
	v_mul_f32_e32 v0, 0x3fb8aa3b, v0
	v_readlane_b32 s10, v254, 45
	v_readlane_b32 s11, v254, 46
	s_cselect_b32 s20, s0, s2
	v_exp_f32_e32 v44, v0
	v_writelane_b32 v254, s8, 43
	s_cmp_lt_i32 s20, 4
	s_cselect_b64 s[2:3], -1, 0
	v_writelane_b32 v254, s9, 44
	v_writelane_b32 v254, s10, 45
	v_writelane_b32 v255, s2, 14
	v_writelane_b32 v254, s11, 46
	s_cmp_gt_i32 s20, 3
	v_writelane_b32 v255, s3, 15
	s_cbranch_scc0 .LBB0_1125
	s_setprio 3
